# SGU: u-tile loads for the next head issued from the previous head's epilogue (prefetch one head ahead), counted waits re-derived
# speedup vs baseline: 1.0068x; 1.0000x over previous
; __device__ __forceinline__ unsigned cvt_pk_bf16(float lo, float hi) { unsigned r; asm volatile("v_cvt_pk_bf16_f32 %0, %1, %2" : "=v"(r) : "v"(lo), "v"(hi)); return r; }
; __device__ __forceinline__ void sgu_phase(const Ctx& C, const bf16_t* Z1, const float* VSS, const float* gv, const bf16_t* WSB, const float* bs, bf16_t* Gout) {
;     ...
;             u32x2 uu[2][4];
; #pragma unroll
;             for (int mt = 0; mt < 2; ++mt)
; #pragma unroll
;                 for (int nt = 0; nt < 4; ++nt) uu[mt][nt] = *(const u32x2*)(Z1 + (size_t)(tok0 + 32 * tb + 16 * mt + fr) * 4096 + 128 * h + 64 * dh + 16 * nt + 4 * g4);
;     ...
; #pragma unroll
;             for (int mt = 0; mt < 2; ++mt) { const int t = 32 * tb + 16 * mt + fr; const float bias = bs[h * 128 + t];
; #pragma unroll
;                 for (int nt = 0; nt < 4; ++nt) { const int d = 128 * h + 64 * dh + 16 * nt + 4 * g4; const u32x2 u2 = uu[mt][nt];
;                     u32x2 o; o.x = cvt_pk_bf16(bflo(u2.x) * (acc[mt][nt][0] + bias), bfhi(u2.x) * (acc[mt][nt][1] + bias)); o.y = cvt_pk_bf16(bflo(u2.y) * (acc[mt][nt][2] + bias), bfhi(u2.y) * (acc[mt][nt][3] + bias));
.LBB0_218:
	s_or_b64 exec, exec, s[22:23]
	v_add_u32_e32 v0, s27, v123
	v_ashrrev_i32_e32 v1, 31, v0
	v_readlane_b32 s0, v254, 11
	v_lshlrev_b64 v[2:3], 13, v[0:1]
	v_readlane_b32 s1, v254, 12
	v_add_u32_e32 v4, 32, v0
	v_mov_b32_e32 v139, v65
	v_lshl_add_u64 v[2:3], s[0:1], 0, v[2:3]
	v_ashrrev_i32_e32 v5, 31, v4
	v_lshl_add_u64 v[2:3], v[2:3], 0, v[138:139]
	s_movk_i32 s22, 0x1000
	v_lshlrev_b64 v[4:5], 13, v[4:5]
	v_add_co_u32_e32 v2, vcc, s22, v2
	v_lshl_add_u64 v[4:5], s[0:1], 0, v[4:5]
	s_nop 0
	v_addc_co_u32_e32 v3, vcc, 0, v3, vcc
	v_lshl_add_u64 v[4:5], v[4:5], 0, v[138:139]
	v_add_co_u32_e32 v4, vcc, s22, v4
	v_ashrrev_i32_e32 v115, 31, v114
	s_nop 0
	v_addc_co_u32_e32 v5, vcc, 0, v5, vcc
	global_load_dwordx4 v[12:15], v[2:3], off
	global_load_dwordx4 v[8:11], v[4:5], off
	v_add_u32_e32 v2, 64, v0
	v_ashrrev_i32_e32 v3, 31, v2
	v_lshlrev_b64 v[2:3], 13, v[2:3]
	v_add_u32_e32 v0, 0x60, v0
	v_lshl_add_u64 v[2:3], s[0:1], 0, v[2:3]
	v_ashrrev_i32_e32 v1, 31, v0
	v_lshl_add_u64 v[2:3], v[2:3], 0, v[138:139]
	v_lshlrev_b64 v[0:1], 13, v[0:1]
	v_add_co_u32_e32 v2, vcc, s22, v2
	v_lshl_add_u64 v[0:1], s[0:1], 0, v[0:1]
	s_nop 0
	v_addc_co_u32_e32 v3, vcc, 0, v3, vcc
	v_lshl_add_u64 v[0:1], v[0:1], 0, v[138:139]
	v_add_co_u32_e32 v0, vcc, 0x1000, v0
	v_lshlrev_b64 v[16:17], 13, v[114:115]
	s_nop 0
	v_addc_co_u32_e32 v1, vcc, 0, v1, vcc
	global_load_dwordx4 v[4:7], v[2:3], off
	s_nop 0
	global_load_dwordx4 v[0:3], v[0:1], off
	v_ashrrev_i32_e32 v117, 31, v116
	v_lshl_add_u64 v[142:143], v[112:113], 0, v[16:17]
	v_lshlrev_b64 v[16:17], 13, v[116:117]
	v_ashrrev_i32_e32 v119, 31, v118
	v_lshl_add_u64 v[144:145], v[112:113], 0, v[16:17]
	v_lshlrev_b64 v[16:17], 13, v[118:119]
	v_ashrrev_i32_e32 v121, 31, v120
	v_lshl_add_u64 v[146:147], v[112:113], 0, v[16:17]
	v_lshlrev_b64 v[16:17], 13, v[120:121]
	v_ashrrev_i32_e32 v127, 31, v126
	v_lshl_add_u64 v[148:149], v[112:113], 0, v[16:17]
	v_ashrrev_i32_e32 v125, 31, v124
	v_lshlrev_b64 v[16:17], 13, v[126:127]
	v_lshlrev_b64 v[150:151], 12, v[124:125]
	v_lshlrev_b64 v[152:153], 12, v[126:127]
	v_lshl_add_u64 v[154:155], v[132:133], 0, v[16:17]
	v_lshlrev_b64 v[16:17], 13, v[124:125]
	v_or_b32_e32 v150, v122, v150
	v_or_b32_e32 v152, v122, v152
	v_lshl_add_u64 v[156:157], v[132:133], 0, v[16:17]
	s_mov_b64 s[0:1], 0
	v_mov_b64_e32 v[158:159], v[136:137]
	v_mov_b64_e32 v[160:161], v[134:135]
	v_mov_b64_e32 v[162:163], v[130:131]
	v_mov_b64_e32 v[164:165], v[128:129]
	v_lshl_add_u64 v[16:17], v[80:81], 0, s[0:1]
	global_load_dwordx4 v[72:75], v[16:17], off
	global_load_dwordx4 v[76:79], v[16:17], off offset:16
	v_lshl_add_u64 v[20:21], s[66:67], 0, v[154:155]
	global_load_dwordx2 v[180:181], v[20:21], off offset:-64
	global_load_dwordx2 v[178:179], v[20:21], off offset:-32
	global_load_dwordx2 v[176:177], v[20:21], off
	global_load_dwordx2 v[174:175], v[20:21], off offset:32
	v_lshl_add_u64 v[20:21], s[66:67], 0, v[156:157]
	global_load_dwordx2 v[172:173], v[20:21], off offset:-64
	global_load_dwordx2 v[170:171], v[20:21], off offset:-32
	global_load_dwordx2 v[168:169], v[20:21], off
	global_load_dwordx2 v[166:167], v[20:21], off offset:32
	s_waitcnt vmcnt(0)
	s_waitcnt lgkmcnt(0)
	s_barrier
	s_branch .LBB0_220
.LBB0_219:
	s_waitcnt vmcnt(1)
	v_lshl_add_u64 v[48:49], v[90:91], 0, s[0:1]
	s_waitcnt vmcnt(0)
	flat_load_dword v52, v[48:49]
	flat_load_dword v70, v[48:49] offset:64
	v_lshl_add_u64 v[50:51], v[80:81], 0, s[0:1]
	global_load_dwordx4 v[72:75], v[50:51], off offset:512
	global_load_dwordx4 v[76:79], v[50:51], off offset:528
	v_lshl_add_u64 v[50:51], s[66:67], 0, v[152:153]
	s_mov_b32 s22, 0x30800000
	s_waitcnt vmcnt(0)
	v_lshlrev_b32_e32 v53, 16, v180
	v_and_b32_e32 v54, 0xffff0000, v180
	v_lshlrev_b32_e32 v55, 16, v181
	v_and_b32_e32 v56, 0xffff0000, v181
	v_lshlrev_b32_e32 v66, 16, v174
	v_and_b32_e32 v67, 0xffff0000, v174
	v_add_co_u32_e32 v50, vcc, s22, v50
	v_lshlrev_b32_e32 v57, 16, v178
	v_and_b32_e32 v58, 0xffff0000, v178
	v_lshlrev_b32_e32 v59, 16, v179
	v_and_b32_e32 v60, 0xffff0000, v179
	v_addc_co_u32_e32 v51, vcc, 0, v51, vcc
	v_lshlrev_b32_e32 v61, 16, v176
	v_and_b32_e32 v62, 0xffff0000, v176
	v_lshlrev_b32_e32 v63, 16, v177
	v_and_b32_e32 v64, 0xffff0000, v177
	v_lshlrev_b32_e32 v68, 16, v175
	v_and_b32_e32 v69, 0xffff0000, v175
	v_lshl_add_u64 v[194:195], s[66:67], 0, v[154:155]
	global_load_dwordx2 v[180:181], v[194:195], off offset:192
	global_load_dwordx2 v[178:179], v[194:195], off offset:224
	global_load_dwordx2 v[176:177], v[194:195], off offset:256
	global_load_dwordx2 v[174:175], v[194:195], off offset:288
	s_mov_b64 vcc, 0x8000
	v_lshl_add_u64 v[164:165], v[164:165], 0, vcc
	v_lshl_add_u64 v[162:163], v[162:163], 0, vcc
	v_lshl_add_u64 v[160:161], v[160:161], 0, vcc
	v_lshl_add_u64 v[158:159], v[158:159], 0, vcc
	s_add_u32 s0, s0, 0x200
	s_mov_b64 s[80:81], 0x100
	s_addc_u32 s1, s1, 0
	v_lshl_add_u64 v[142:143], v[142:143], 0, s[80:81]
	v_lshl_add_u64 v[144:145], v[144:145], 0, s[80:81]
	v_lshl_add_u64 v[146:147], v[146:147], 0, s[80:81]
	v_lshl_add_u64 v[148:149], v[148:149], 0, s[80:81]
	v_lshl_add_u64 v[152:153], v[152:153], 0, s[80:81]
	v_lshl_add_u64 v[154:155], v[154:155], 0, s[80:81]
	s_cmpk_eq_i32 s0, 0x1e00
	v_lshl_add_u64 v[156:157], v[156:157], 0, s[80:81]
	s_waitcnt lgkmcnt(0)
; #define LAS __attribute__((address_space(3)))
; __device__ __forceinline__ unsigned cvt_pk_bf16(float lo, float hi) { unsigned r; asm volatile("v_cvt_pk_bf16_f32 %0, %1, %2" : "=v"(r) : "v"(lo), "v"(hi)); return r; }
; __device__ __forceinline__ void sgu_phase(const Ctx& C, const bf16_t* Z1, const float* VSS, const float* gv, const bf16_t* WSB, const float* bs, bf16_t* Gout) {
;     ...
;         for (int h = 0; h < 16; ++h) {
;             {
;                 const f32x4 ga = *(const f32x4*)(gv + 128 * h + 8 * ch), gb = *(const f32x4*)(gv + 128 * h + 8 * ch + 4);
; #pragma unroll
;                 for (int ps = 0; ps < 4; ++ps) { const int s = ps * 32 + srow; const u32x4 raw = vraw[ps]; const float r = rsv[s];
;                     u32x4 o; o.x = cvt_pk_bf16(bflo(raw.x) * r * ga[0], bfhi(raw.x) * r * ga[1]); o.y = cvt_pk_bf16(bflo(raw.y) * r * ga[2], bfhi(raw.y) * r * ga[3]);
;                     o.z = cvt_pk_bf16(bflo(raw.z) * r * gb[0], bfhi(raw.z) * r * gb[1]); o.w = cvt_pk_bf16(bflo(raw.w) * r * gb[2], bfhi(raw.w) * r * gb[3]);
;                     *(LAS u32x4*)(Vs + off_b(s, ch)) = o; }
;     ...
; #pragma unroll
;             for (int mt = 0; mt < 2; ++mt) { const int t = 32 * tb + 16 * mt + fr; const float bias = bs[h * 128 + t];
; #pragma unroll
;                 for (int nt = 0; nt < 4; ++nt) { const int d = 128 * h + 64 * dh + 16 * nt + 4 * g4; const u32x2 u2 = uu[mt][nt];
;                     u32x2 o; o.x = cvt_pk_bf16(bflo(u2.x) * (acc[mt][nt][0] + bias), bfhi(u2.x) * (acc[mt][nt][1] + bias)); o.y = cvt_pk_bf16(bflo(u2.y) * (acc[mt][nt][2] + bias), bfhi(u2.y) * (acc[mt][nt][3] + bias));
;                     *(u32x2*)(Gout + (size_t)(tok0 + t) * DM + d) = o; } }
	v_add_f32_e32 v44, v52, v44
	v_add_f32_e32 v45, v52, v45
	v_add_f32_e32 v46, v52, v46
	v_add_f32_e32 v47, v52, v47
	v_add_f32_e32 v32, v32, v52
	v_add_f32_e32 v33, v33, v52
	v_add_f32_e32 v40, v40, v52
	v_add_f32_e32 v41, v41, v52
	v_add_f32_e32 v42, v42, v52
	v_add_f32_e32 v43, v43, v52
	v_add_f32_e32 v36, v36, v52
	v_add_f32_e32 v37, v37, v52
	v_add_f32_e32 v38, v38, v52
	v_add_f32_e32 v39, v39, v52
	v_add_f32_e32 v34, v34, v52
	v_add_f32_e32 v35, v35, v52
	v_mul_f32_e32 v44, v44, v53
	v_mul_f32_e32 v45, v45, v54
	v_mul_f32_e32 v46, v46, v55
	v_mul_f32_e32 v47, v47, v56
	v_mul_f32_e32 v52, v32, v66
	v_mul_f32_e32 v53, v33, v67
	v_cvt_pk_bf16_f32 v32, v44, v45
	v_cvt_pk_bf16_f32 v33, v46, v47
	v_mul_f32_e32 v40, v40, v57
	v_mul_f32_e32 v41, v41, v58
	v_mul_f32_e32 v42, v42, v59
	v_mul_f32_e32 v43, v43, v60
	global_store_dwordx2 v[50:51], v[32:33], off
	v_cvt_pk_bf16_f32 v32, v40, v41
	v_cvt_pk_bf16_f32 v33, v42, v43
	v_mul_f32_e32 v36, v36, v61
	v_mul_f32_e32 v37, v37, v62
	v_mul_f32_e32 v38, v38, v63
	v_mul_f32_e32 v39, v39, v64
	global_store_dwordx2 v[50:51], v[32:33], off offset:32
	v_cvt_pk_bf16_f32 v32, v36, v37
	v_cvt_pk_bf16_f32 v33, v38, v39
	v_mul_f32_e32 v34, v34, v68
	v_mul_f32_e32 v35, v35, v69
	global_store_dwordx2 v[50:51], v[32:33], off offset:64
	v_cvt_pk_bf16_f32 v32, v52, v53
	v_cvt_pk_bf16_f32 v33, v34, v35
	global_store_dwordx2 v[50:51], v[32:33], off offset:96
	v_lshl_add_u64 v[32:33], s[66:67], 0, v[150:151]
	v_lshlrev_b32_e32 v35, 16, v172
	v_and_b32_e32 v36, 0xffff0000, v172
	v_lshlrev_b32_e32 v37, 16, v173
	v_and_b32_e32 v38, 0xffff0000, v173
	v_lshlrev_b32_e32 v47, 16, v166
	v_and_b32_e32 v48, 0xffff0000, v166
	v_add_co_u32_e32 v32, vcc, s22, v32
	v_lshlrev_b32_e32 v39, 16, v170
	v_and_b32_e32 v40, 0xffff0000, v170
	v_lshlrev_b32_e32 v41, 16, v171
	v_and_b32_e32 v42, 0xffff0000, v171
	v_addc_co_u32_e32 v33, vcc, 0, v33, vcc
	v_lshlrev_b32_e32 v43, 16, v168
	v_and_b32_e32 v44, 0xffff0000, v168
	v_lshlrev_b32_e32 v45, 16, v169
	v_and_b32_e32 v46, 0xffff0000, v169
	v_lshlrev_b32_e32 v49, 16, v167
	v_and_b32_e32 v50, 0xffff0000, v167
	v_lshl_add_u64 v[194:195], s[66:67], 0, v[156:157]
	global_load_dwordx2 v[172:173], v[194:195], off offset:-64
	global_load_dwordx2 v[170:171], v[194:195], off offset:-32
	global_load_dwordx2 v[168:169], v[194:195], off
	global_load_dwordx2 v[166:167], v[194:195], off offset:32
	v_lshl_add_u64 v[150:151], v[150:151], 0, s[80:81]
	v_add_f32_e32 v28, v28, v70
	v_add_f32_e32 v29, v29, v70
	v_add_f32_e32 v30, v30, v70
	v_add_f32_e32 v31, v31, v70
	v_add_f32_e32 v16, v16, v70
	v_add_f32_e32 v17, v17, v70
	v_add_f32_e32 v24, v24, v70
	v_add_f32_e32 v25, v25, v70
	v_add_f32_e32 v26, v26, v70
	v_add_f32_e32 v27, v27, v70
	v_add_f32_e32 v20, v20, v70
	v_add_f32_e32 v21, v21, v70
	v_add_f32_e32 v22, v22, v70
	v_add_f32_e32 v23, v23, v70
	v_add_f32_e32 v18, v18, v70
	v_add_f32_e32 v19, v19, v70
	v_mul_f32_e32 v28, v28, v35
	v_mul_f32_e32 v29, v29, v36
	v_mul_f32_e32 v30, v30, v37
	v_mul_f32_e32 v31, v31, v38
	v_mul_f32_e32 v34, v16, v47
	v_mul_f32_e32 v35, v17, v48
	v_cvt_pk_bf16_f32 v16, v28, v29
	v_cvt_pk_bf16_f32 v17, v30, v31
	v_mul_f32_e32 v24, v24, v39
	v_mul_f32_e32 v25, v25, v40
	v_mul_f32_e32 v26, v26, v41
	v_mul_f32_e32 v27, v27, v42
	global_store_dwordx2 v[32:33], v[16:17], off
	v_cvt_pk_bf16_f32 v16, v24, v25
	v_cvt_pk_bf16_f32 v17, v26, v27
	v_mul_f32_e32 v20, v20, v43
	v_mul_f32_e32 v21, v21, v44
	v_mul_f32_e32 v22, v22, v45
	v_mul_f32_e32 v23, v23, v46
	global_store_dwordx2 v[32:33], v[16:17], off offset:32
	v_cvt_pk_bf16_f32 v16, v20, v21
	v_cvt_pk_bf16_f32 v17, v22, v23
	v_mul_f32_e32 v18, v18, v49
	v_mul_f32_e32 v19, v19, v50
	global_store_dwordx2 v[32:33], v[16:17], off offset:64
	v_cvt_pk_bf16_f32 v16, v34, v35
	v_cvt_pk_bf16_f32 v17, v18, v19
	global_store_dwordx2 v[32:33], v[16:17], off offset:96
	s_barrier
	s_cbranch_scc1 .LBB0_228
.LBB0_220:
	v_mov_b64_e32 v[20:21], v[72:73]
	v_mov_b64_e32 v[22:23], v[74:75]
	v_mov_b64_e32 v[16:17], v[76:77]
	v_mov_b64_e32 v[18:19], v[78:79]
	ds_read_b32 v24, v183 offset:32768
	v_lshlrev_b32_e32 v25, 16, v12
	v_and_b32_e32 v12, 0xffff0000, v12
	v_add_u32_e32 v115, v182, v184
	s_mov_b32 s22, 0x1f01000
	s_waitcnt lgkmcnt(0)
	v_mul_f32_e32 v25, v24, v25
	v_mul_f32_e32 v12, v24, v12
	v_mul_f32_e32 v25, v20, v25
	v_mul_f32_e32 v12, v21, v12
	v_cvt_pk_bf16_f32 v12, v25, v12
	v_lshlrev_b32_e32 v25, 16, v13
	v_and_b32_e32 v13, 0xffff0000, v13
	v_mul_f32_e32 v25, v24, v25
	v_mul_f32_e32 v13, v24, v13
	v_mul_f32_e32 v25, v22, v25
	v_mul_f32_e32 v13, v23, v13
	v_cvt_pk_bf16_f32 v13, v25, v13
	v_lshlrev_b32_e32 v25, 16, v14
	v_and_b32_e32 v14, 0xffff0000, v14
	v_mul_f32_e32 v25, v24, v25
	v_mul_f32_e32 v14, v24, v14
	v_mul_f32_e32 v25, v16, v25
	v_mul_f32_e32 v14, v17, v14
	v_cvt_pk_bf16_f32 v14, v25, v14
	v_lshlrev_b32_e32 v25, 16, v15
	v_and_b32_e32 v15, 0xffff0000, v15
	v_mul_f32_e32 v15, v24, v15
	v_mul_f32_e32 v25, v24, v25
	v_mul_f32_e32 v15, v19, v15
	v_mul_f32_e32 v25, v18, v25
	v_cvt_pk_bf16_f32 v15, v25, v15
	ds_write_b128 v115, v[12:15]
	ds_read_b32 v12, v183 offset:32896
	v_lshlrev_b32_e32 v13, 16, v8
	v_and_b32_e32 v8, 0xffff0000, v8
	s_waitcnt lgkmcnt(0)
	v_mul_f32_e32 v13, v12, v13
	v_mul_f32_e32 v8, v12, v8
	v_mul_f32_e32 v13, v20, v13
	v_mul_f32_e32 v8, v21, v8
	v_cvt_pk_bf16_f32 v8, v13, v8
	v_lshlrev_b32_e32 v13, 16, v9
	v_and_b32_e32 v9, 0xffff0000, v9
	v_mul_f32_e32 v13, v12, v13
	v_mul_f32_e32 v9, v12, v9
	v_mul_f32_e32 v13, v22, v13
	v_mul_f32_e32 v9, v23, v9
	v_cvt_pk_bf16_f32 v9, v13, v9
	v_lshlrev_b32_e32 v13, 16, v10
	v_and_b32_e32 v10, 0xffff0000, v10
	v_mul_f32_e32 v13, v12, v13
	v_mul_f32_e32 v10, v12, v10
	v_mul_f32_e32 v13, v16, v13
	v_mul_f32_e32 v10, v17, v10
	v_cvt_pk_bf16_f32 v10, v13, v10
	v_lshlrev_b32_e32 v13, 16, v11
	v_and_b32_e32 v11, 0xffff0000, v11
	v_mul_f32_e32 v11, v12, v11
	v_mul_f32_e32 v13, v12, v13
	v_mul_f32_e32 v11, v19, v11
	v_mul_f32_e32 v13, v18, v13
	v_cvt_pk_bf16_f32 v11, v13, v11
	ds_write_b128 v230, v[8:11]
	ds_read_b32 v8, v183 offset:33024
	v_lshlrev_b32_e32 v9, 16, v4
	v_and_b32_e32 v4, 0xffff0000, v4
	s_waitcnt lgkmcnt(0)
; #define LAS __attribute__((address_space(3)))
; __device__ __forceinline__ void sgu_phase(const Ctx& C, const bf16_t* Z1, const float* VSS, const float* gv, const bf16_t* WSB, const float* bs, bf16_t* Gout) {
;     ...
;                 for (int ps = 0; ps < 4; ++ps) { const int s = ps * 32 + srow; const u32x4 raw = vraw[ps]; const float r = rsv[s];
;                     u32x4 o; o.x = cvt_pk_bf16(bflo(raw.x) * r * ga[0], bfhi(raw.x) * r * ga[1]); o.y = cvt_pk_bf16(bflo(raw.y) * r * ga[2], bfhi(raw.y) * r * ga[3]);
;                     o.z = cvt_pk_bf16(bflo(raw.z) * r * gb[0], bfhi(raw.z) * r * gb[1]); o.w = cvt_pk_bf16(bflo(raw.w) * r * gb[2], bfhi(raw.w) * r * gb[3]);
;                     *(LAS u32x4*)(Vs + off_b(s, ch)) = o; }
;             }
;             if (h + 1 < 16) {
; #pragma unroll
;                 for (int ps = 0; ps < 4; ++ps) vraw[ps] = *(const u32x4*)(Z1 + (size_t)(tok0 + ps * 32 + srow) * 4096 + 2048 + 128 * (h + 1) + 8 * ch);
;             }
;             bf16x8 wf[4][2];
; #pragma unroll
;             for (int kk = 0; kk < 4; ++kk)
; #pragma unroll
;                 for (int mt = 0; mt < 2; ++mt) wf[kk][mt] = *(const bf16x8*)(WSB + ((size_t)h * 128 + 32 * tb + 16 * mt + fr) * 128 + 32 * (kk <= tb ? kk : tb) + 8 * g4);
;             u32x2 uu[2][4];
; #pragma unroll
;             for (int mt = 0; mt < 2; ++mt)
; #pragma unroll
;                 for (int nt = 0; nt < 4; ++nt) uu[mt][nt] = *(const u32x2*)(Z1 + (size_t)(tok0 + 32 * tb + 16 * mt + fr) * 4096 + 128 * h + 64 * dh + 16 * nt + 4 * g4);
;             __syncthreads();
;             f32x4 acc[2][4];
; #pragma unroll
;             for (int a = 0; a < 2; ++a)
; #pragma unroll
;                 for (int b = 0; b < 4; ++b) acc[a][b] = (f32x4){0.f, 0.f, 0.f, 0.f};
; #pragma unroll
;             for (int kk = 0; kk < 4; ++kk) {
;                 if (kk <= tb) {
;                     unsigned ad[8]; bf16x8 vf[4];
; #pragma unroll
;                     for (int nt = 0; nt < 4; ++nt) { ad[2 * nt] = ldsbase + tr_read_addr_16(lane, 4 * dh + nt, kk, 0); ad[2 * nt + 1] = ldsbase + tr_read_addr_16(lane, 4 * dh + nt, kk, 1); }
;                     tr_read8(vf, ad);
; #pragma unroll
;                     for (int nt = 0; nt < 4; ++nt)
; #pragma unroll
;                         for (int mt = 0; mt < 2; ++mt) acc[mt][nt] = __builtin_amdgcn_mfma_f32_16x16x32_bf16(vf[nt], wf[kk][mt], acc[mt][nt], 0, 0, 0);
	v_mul_f32_e32 v9, v8, v9
	v_mul_f32_e32 v4, v8, v4
	v_mul_f32_e32 v9, v20, v9
	v_mul_f32_e32 v4, v21, v4
	v_cvt_pk_bf16_f32 v4, v9, v4
	v_lshlrev_b32_e32 v9, 16, v5
	v_and_b32_e32 v5, 0xffff0000, v5
	v_mul_f32_e32 v9, v8, v9
	v_mul_f32_e32 v5, v8, v5
	v_mul_f32_e32 v9, v22, v9
	v_mul_f32_e32 v5, v23, v5
	v_cvt_pk_bf16_f32 v5, v9, v5
	v_lshlrev_b32_e32 v9, 16, v6
	v_and_b32_e32 v6, 0xffff0000, v6
	v_mul_f32_e32 v9, v8, v9
	v_mul_f32_e32 v6, v8, v6
	v_mul_f32_e32 v9, v16, v9
	v_mul_f32_e32 v6, v17, v6
	v_cvt_pk_bf16_f32 v6, v9, v6
	v_lshlrev_b32_e32 v9, 16, v7
	v_and_b32_e32 v7, 0xffff0000, v7
	v_mul_f32_e32 v7, v8, v7
	v_mul_f32_e32 v9, v8, v9
	v_mul_f32_e32 v7, v19, v7
	v_mul_f32_e32 v9, v18, v9
	v_cvt_pk_bf16_f32 v7, v9, v7
	ds_write_b128 v231, v[4:7]
	ds_read_b32 v4, v183 offset:33152
	v_lshlrev_b32_e32 v5, 16, v0
	v_and_b32_e32 v0, 0xffff0000, v0
	s_waitcnt lgkmcnt(0)
	v_mul_f32_e32 v5, v4, v5
	v_mul_f32_e32 v0, v4, v0
	v_mul_f32_e32 v5, v20, v5
	v_mul_f32_e32 v0, v21, v0
	v_cvt_pk_bf16_f32 v0, v5, v0
	v_lshlrev_b32_e32 v5, 16, v1
	v_and_b32_e32 v1, 0xffff0000, v1
	v_mul_f32_e32 v5, v4, v5
	v_mul_f32_e32 v1, v4, v1
	v_mul_f32_e32 v5, v22, v5
	v_mul_f32_e32 v1, v23, v1
	v_cvt_pk_bf16_f32 v1, v5, v1
	v_lshlrev_b32_e32 v5, 16, v2
	v_and_b32_e32 v2, 0xffff0000, v2
	v_mul_f32_e32 v5, v4, v5
	v_mul_f32_e32 v2, v4, v2
	v_mul_f32_e32 v5, v16, v5
	v_mul_f32_e32 v2, v17, v2
	v_cvt_pk_bf16_f32 v2, v5, v2
	v_lshlrev_b32_e32 v5, 16, v3
	v_and_b32_e32 v3, 0xffff0000, v3
	v_mul_f32_e32 v3, v4, v3
	v_mul_f32_e32 v5, v4, v5
	v_mul_f32_e32 v3, v19, v3
	v_mul_f32_e32 v5, v18, v5
	v_cvt_pk_bf16_f32 v3, v5, v3
	ds_write_b128 v232, v[0:3]
	v_lshl_add_u64 v[0:1], s[66:67], 0, v[142:143]
	global_load_dwordx4 v[12:15], v[0:1], off
	v_lshl_add_u64 v[0:1], s[66:67], 0, v[144:145]
	v_lshl_add_u64 v[16:17], s[66:67], 0, v[158:159]
	global_load_dwordx4 v[8:11], v[0:1], off
	v_lshl_add_u64 v[0:1], s[66:67], 0, v[146:147]
	v_add_co_u32_e32 v20, vcc, s22, v16
	global_load_dwordx4 v[4:7], v[0:1], off
	v_lshl_add_u64 v[0:1], s[66:67], 0, v[148:149]
	v_addc_co_u32_e32 v21, vcc, 0, v17, vcc
	global_load_dwordx4 v[0:3], v[0:1], off
	s_nop 0
	global_load_dwordx4 v[16:19], v[20:21], off offset:-4096
	global_load_dwordx4 v[76:79], v[20:21], off
	v_lshl_add_u64 v[20:21], s[66:67], 0, v[160:161]
	v_add_co_u32_e32 v20, vcc, s22, v20
	s_nop 1
	v_addc_co_u32_e32 v21, vcc, 0, v21, vcc
	global_load_dwordx4 v[68:71], v[20:21], off offset:-4096
	global_load_dwordx4 v[72:75], v[20:21], off
	v_lshl_add_u64 v[20:21], s[66:67], 0, v[162:163]
	v_add_co_u32_e32 v20, vcc, s22, v20
	s_nop 1
	v_addc_co_u32_e32 v21, vcc, 0, v21, vcc
	global_load_dwordx4 v[56:59], v[20:21], off offset:-4096
	global_load_dwordx4 v[60:63], v[20:21], off
	v_lshl_add_u64 v[20:21], s[66:67], 0, v[164:165]
	v_add_co_u32_e32 v20, vcc, s22, v20
	s_nop 1
	v_addc_co_u32_e32 v21, vcc, 0, v21, vcc
	global_load_dwordx4 v[48:51], v[20:21], off offset:-4096
	global_load_dwordx4 v[52:55], v[20:21], off
	v_cndmask_b32_e64 v20, 0, 1, s[54:55]
	v_cmp_ne_u32_e64 s[40:41], 1, v20
	s_andn2_b64 vcc, exec, s[54:55]
	s_waitcnt lgkmcnt(0)
	s_barrier
	s_cbranch_vccnz .LBB0_222
	ds_read_b64_tr_b16 v[28:29], v185
	ds_read_b64_tr_b16 v[30:31], v186
	ds_read_b64_tr_b16 v[24:25], v187
	ds_read_b64_tr_b16 v[26:27], v188
	ds_read_b64_tr_b16 v[20:21], v189
	ds_read_b64_tr_b16 v[22:23], v190
	ds_read_b64_tr_b16 v[234:235], v191
	ds_read_b64_tr_b16 v[236:237], v192
	s_waitcnt lgkmcnt(0)
	s_waitcnt vmcnt(7)
	v_mfma_f32_16x16x32_bf16 v[44:47], v[28:31], v[16:19], 0
	s_waitcnt vmcnt(6)
	v_mfma_f32_16x16x32_bf16 v[28:31], v[28:31], v[76:79], 0
	v_mfma_f32_16x16x32_bf16 v[40:43], v[24:27], v[16:19], 0
	v_mfma_f32_16x16x32_bf16 v[24:27], v[24:27], v[76:79], 0
	v_mfma_f32_16x16x32_bf16 v[36:39], v[20:23], v[16:19], 0
	v_mfma_f32_16x16x32_bf16 v[20:23], v[20:23], v[76:79], 0
	v_mfma_f32_16x16x32_bf16 v[32:35], v[234:237], v[16:19], 0
	v_mfma_f32_16x16x32_bf16 v[16:19], v[234:237], v[76:79], 0
	v_cndmask_b32_e64 v64, 0, 1, s[56:57]
	v_cmp_ne_u32_e64 s[42:43], 1, v64
	s_andn2_b64 vcc, exec, s[56:57]
	s_cbranch_vccz .LBB0_223
	s_branch .LBB0_224
; __device__ __forceinline__ void sgu_phase(const Ctx& C, const bf16_t* Z1, const float* VSS, const float* gv, const bf16_t* WSB, const float* bs, bf16_t* Gout) {
;     ...
; #pragma unroll
;             for (int kk = 0; kk < 4; ++kk) {
;                 if (kk <= tb) {
;                     unsigned ad[8]; bf16x8 vf[4];
; #pragma unroll
;                     for (int nt = 0; nt < 4; ++nt) { ad[2 * nt] = ldsbase + tr_read_addr_16(lane, 4 * dh + nt, kk, 0); ad[2 * nt + 1] = ldsbase + tr_read_addr_16(lane, 4 * dh + nt, kk, 1); }
;                     tr_read8(vf, ad);
; #pragma unroll
;                     for (int nt = 0; nt < 4; ++nt)
; #pragma unroll
;                         for (int mt = 0; mt < 2; ++mt) acc[mt][nt] = __builtin_amdgcn_mfma_f32_16x16x32_bf16(vf[nt], wf[kk][mt], acc[mt][nt], 0, 0, 0);
;                 }
.LBB0_222:
	v_mov_b32_e32 v64, v65
	v_mov_b32_e32 v66, v65
	v_mov_b32_e32 v67, v65
	s_waitcnt vmcnt(7)
	v_mov_b64_e32 v[16:17], v[64:65]
	v_mov_b64_e32 v[20:21], v[64:65]
	v_mov_b64_e32 v[24:25], v[64:65]
	v_mov_b64_e32 v[28:29], v[64:65]
	v_mov_b64_e32 v[32:33], v[64:65]
	v_mov_b64_e32 v[36:37], v[64:65]
	v_mov_b64_e32 v[40:41], v[64:65]
	v_mov_b64_e32 v[44:45], v[64:65]
	v_mov_b64_e32 v[18:19], v[66:67]
	v_mov_b64_e32 v[22:23], v[66:67]
	v_mov_b64_e32 v[26:27], v[66:67]
	v_mov_b64_e32 v[30:31], v[66:67]
	v_mov_b64_e32 v[34:35], v[66:67]
	v_mov_b64_e32 v[38:39], v[66:67]
	v_mov_b64_e32 v[42:43], v[66:67]
	v_mov_b64_e32 v[46:47], v[66:67]
	v_cndmask_b32_e64 v64, 0, 1, s[56:57]
	v_cmp_ne_u32_e64 s[42:43], 1, v64
	s_andn2_b64 vcc, exec, s[56:57]
	s_cbranch_vccnz .LBB0_224
.LBB0_223:
	s_waitcnt vmcnt(6)
	ds_read_b64_tr_b16 v[194:195], v193
	ds_read_b64_tr_b16 v[196:197], v206
	ds_read_b64_tr_b16 v[244:245], v207
	ds_read_b64_tr_b16 v[246:247], v208
	ds_read_b64_tr_b16 v[234:235], v209
	ds_read_b64_tr_b16 v[236:237], v210
	ds_read_b64_tr_b16 v[76:77], v211
	ds_read_b64_tr_b16 v[78:79], v212
	s_waitcnt lgkmcnt(0)
	s_waitcnt vmcnt(5)
	v_mfma_f32_16x16x32_bf16 v[44:47], v[194:197], v[68:71], v[44:47]
	s_waitcnt vmcnt(4)
	v_mfma_f32_16x16x32_bf16 v[28:31], v[194:197], v[72:75], v[28:31]
	v_mfma_f32_16x16x32_bf16 v[40:43], v[244:247], v[68:71], v[40:43]
	v_mfma_f32_16x16x32_bf16 v[24:27], v[244:247], v[72:75], v[24:27]
	v_mfma_f32_16x16x32_bf16 v[36:39], v[234:237], v[68:71], v[36:39]
	v_mfma_f32_16x16x32_bf16 v[20:23], v[234:237], v[72:75], v[20:23]
	v_mfma_f32_16x16x32_bf16 v[32:35], v[76:79], v[68:71], v[32:35]
	v_mfma_f32_16x16x32_bf16 v[16:19], v[76:79], v[72:75], v[16:19]
.LBB0_224:
	v_cndmask_b32_e64 v64, 0, 1, s[58:59]
	v_cmp_ne_u32_e64 s[44:45], 1, v64
	s_andn2_b64 vcc, exec, s[58:59]
	s_cbranch_vccnz .LBB0_226
	s_waitcnt vmcnt(4)
	ds_read_b64_tr_b16 v[194:195], v213
	ds_read_b64_tr_b16 v[196:197], v214
	ds_read_b64_tr_b16 v[74:75], v215
	ds_read_b64_tr_b16 v[76:77], v216
	ds_read_b64_tr_b16 v[70:71], v217
	ds_read_b64_tr_b16 v[72:73], v218
	ds_read_b64_tr_b16 v[66:67], v219
	ds_read_b64_tr_b16 v[68:69], v220
	s_waitcnt lgkmcnt(0)
	s_waitcnt vmcnt(3)
	v_mfma_f32_16x16x32_bf16 v[44:47], v[194:197], v[56:59], v[44:47]
	s_waitcnt vmcnt(2)
	v_mfma_f32_16x16x32_bf16 v[28:31], v[194:197], v[60:63], v[28:31]
	v_mfma_f32_16x16x32_bf16 v[40:43], v[74:77], v[56:59], v[40:43]
	v_mfma_f32_16x16x32_bf16 v[24:27], v[74:77], v[60:63], v[24:27]
	v_mfma_f32_16x16x32_bf16 v[36:39], v[70:73], v[56:59], v[36:39]
	v_mfma_f32_16x16x32_bf16 v[20:23], v[70:73], v[60:63], v[20:23]
	v_mfma_f32_16x16x32_bf16 v[32:35], v[66:69], v[56:59], v[32:35]
	v_mfma_f32_16x16x32_bf16 v[16:19], v[66:69], v[60:63], v[16:19]
	v_cndmask_b32_e64 v56, 0, 1, s[70:71]
	v_cmp_ne_u32_e64 s[46:47], 1, v56
	s_andn2_b64 vcc, exec, s[70:71]
	s_cbranch_vccnz .LBB0_219
	s_branch .LBB0_227
.LBB0_226:
	s_waitcnt vmcnt(3)
	v_cndmask_b32_e64 v56, 0, 1, s[70:71]
	v_cmp_ne_u32_e64 s[46:47], 1, v56
	s_andn2_b64 vcc, exec, s[70:71]
	s_cbranch_vccnz .LBB0_219
.LBB0_227:
	s_waitcnt vmcnt(2)
	ds_read_b64_tr_b16 v[70:71], v221
	ds_read_b64_tr_b16 v[72:73], v222
	ds_read_b64_tr_b16 v[66:67], v223
	ds_read_b64_tr_b16 v[68:69], v224
	ds_read_b64_tr_b16 v[60:61], v225
	ds_read_b64_tr_b16 v[62:63], v226
	ds_read_b64_tr_b16 v[56:57], v227
	ds_read_b64_tr_b16 v[58:59], v228
	s_waitcnt lgkmcnt(0)
	s_waitcnt vmcnt(1)
	v_mfma_f32_16x16x32_bf16 v[44:47], v[70:73], v[48:51], v[44:47]
	s_waitcnt vmcnt(0)
	v_mfma_f32_16x16x32_bf16 v[28:31], v[70:73], v[52:55], v[28:31]
	v_mfma_f32_16x16x32_bf16 v[40:43], v[66:69], v[48:51], v[40:43]
	v_mfma_f32_16x16x32_bf16 v[24:27], v[66:69], v[52:55], v[24:27]
	v_mfma_f32_16x16x32_bf16 v[36:39], v[60:63], v[48:51], v[36:39]
	v_mfma_f32_16x16x32_bf16 v[20:23], v[60:63], v[52:55], v[20:23]
	v_mfma_f32_16x16x32_bf16 v[32:35], v[56:59], v[48:51], v[32:35]
	v_mfma_f32_16x16x32_bf16 v[16:19], v[56:59], v[52:55], v[16:19]
	s_branch .LBB0_219
